# scan chains: one scalar base per chunk + single v_mad per output store / next-chunk load instead of 7-instruction row address
# speedup vs baseline: 1.0920x; 1.0061x over previous
; DI int crow(int r, int h) { return (r & 3) + 8 * (r >> 2) + 4 * h; }
; DI int opaque_tid() { int t = threadIdx.x; asm volatile("" : "+v"(t)); return t; }
; DI void stream_of(int n, int cpc, int& m, int& T, int& soff) { if (n < cpc) { m = n; T = CTX; soff = 0; } else { m = n - cpc; T = SEQ; soff = CTX; } }
; DI void hg_scan_block(const Params& p, int chain_in, unsigned char* smem) {
;     ...
;   const int tid = opaque_tid(), lane = tid & 63, sl = tid >> 6, l31 = lane & 31, h = lane >> 5;
;   const int hd = chain & 3, b = (chain >> 2) & 3, dir = chain >> 4;
;   float* OHG = (float*)(WS_ + O_OHG) + (size_t)dir * NTOK * 512;
;   bfr* sU = (bfr*)smem;
;   const bfr *s_qhat = sU, *s_khT = sU + 4096, *s_vT = sU + 8192;
;   float* s_ds = (float*)(smem + 24576);
;   const u32x4* src = (const u32x4*)(WS_ + O_HGU) + (size_t)chain * 136 * 1536;
;   const float* dsg = (const float*)(WS_ + O_HGD) + (size_t)chain * 136 * 128;
;   u32x4 st[6]; float dsr;
; #pragma unroll
;   for (int i = 0; i < 6; ++i) st[i] = src[tid + 256 * i];
;   dsr = dsg[tid & 127];
;   float oc[16];
;   {
;     int m0_, T0_, so0_; stream_of(0, 8, m0_, T0_, so0_);
; #pragma unroll
;     for (int r = 0; r < 16; ++r) {
;       const int pos = 32 * m0_ + crow(r, h), t = dir ? T0_ - 1 - pos : pos;
;       oc[r] = OHG[(size_t)(b * SP + so0_ + t) * 512 + hd * 128 + 32 * sl + l31];
;     }
;   }
.LBB0_494:
	s_or_b64 exec, exec, s[4:5]
	v_readlane_b32 s6, v255, 1
	v_readlane_b32 s7, v255, 2
	v_mov_b32_e32 v211, v216
	s_mov_b64 s[4:5], -1
	s_and_b64 vcc, exec, s[6:7]
	s_mov_b32 s37, 0x800000
	s_barrier
	s_cbranch_vccz .LBB0_505
	v_readlane_b32 s4, v255, 35
	v_readlane_b32 s5, v255, 36
	s_andn2_b64 vcc, exec, s[4:5]
	s_cbranch_vccnz .LBB0_504
	v_readlane_b32 s4, v254, 28
	s_nop 1
	v_mov_b32_e32 v0, s4
	s_mov_b64 s[4:5], s[84:85]
	v_readfirstlane_b32 s8, v0
	s_sub_i32 s9, s8, 32
	s_ashr_i32 s6, s9, 4
	s_mul_hi_i32 s10, s6, 0x2200000
	s_mul_i32 s11, s6, 0x2200000
	s_mul_i32 s6, s9, 0x330000
	v_mov_b32_e32 v0, v216
	s_mul_hi_i32 s7, s9, 0x330000
	s_add_u32 s6, s4, s6
	s_addc_u32 s7, s5, s7
	v_ashrrev_i32_e32 v1, 31, v0
	v_lshl_add_u64 v[104:105], v[0:1], 4, s[6:7]
	s_mov_b32 s6, 0x619cf000
	v_add_co_u32_e32 v2, vcc, s6, v104
	s_mov_b32 s6, 0x619d0000
	s_nop 0
	v_addc_co_u32_e32 v3, vcc, 0, v105, vcc
	v_add_co_u32_e32 v4, vcc, s6, v104
	s_mov_b32 s6, 0x619d1000
	s_nop 0
	v_addc_co_u32_e32 v5, vcc, 0, v105, vcc
	global_load_dwordx4 v[80:83], v[2:3], off offset:1536
	global_load_dwordx4 v[84:87], v[4:5], off offset:1536
	v_add_co_u32_e32 v2, vcc, s6, v104
	s_mov_b32 s6, 0x619d2000
	s_nop 0
	v_addc_co_u32_e32 v3, vcc, 0, v105, vcc
	v_add_co_u32_e32 v4, vcc, s6, v104
	s_mov_b32 s6, 0x619d3000
	s_nop 0
	v_addc_co_u32_e32 v5, vcc, 0, v105, vcc
	global_load_dwordx4 v[88:91], v[2:3], off offset:1536
	global_load_dwordx4 v[92:95], v[4:5], off offset:1536
	v_add_co_u32_e32 v2, vcc, s6, v104
	s_bfe_u32 s22, s8, 0x20002
	s_nop 0
	v_addc_co_u32_e32 v3, vcc, 0, v105, vcc
	s_mov_b32 s6, 0x619d4000
	s_add_u32 s11, s4, s11
	s_mul_i32 s21, s9, 0x11000
	v_add_co_u32_e32 v4, vcc, s6, v104
	s_addc_u32 s10, s5, s10
	s_mul_hi_i32 s20, s9, 0x11000
	v_addc_co_u32_e32 v5, vcc, 0, v105, vcc
	global_load_dwordx4 v[96:99], v[2:3], off offset:1536
	global_load_dwordx4 v[100:103], v[4:5], off offset:1536
	v_and_b32_e32 v2, 0x7f, v0
	s_add_u32 s4, s4, s21
	v_lshlrev_b32_e32 v208, 2, v2
	s_addc_u32 s5, s5, s20
	v_lshl_add_u64 v[2:3], s[4:5], 0, v[208:209]
	s_mov_b32 s4, 0x67fcf000
	s_cmp_lt_u32 s9, 16
	v_bfe_u32 v21, v0, 5, 1
	v_add_co_u32_e32 v4, vcc, s4, v2
	s_cselect_b64 s[6:7], -1, 0
	s_lshl_b32 s4, s8, 9
	v_ashrrev_i32_e32 v20, 6, v0
	v_lshlrev_b32_e32 v110, 2, v21
	s_and_b32 s4, s4, 0x600
	v_and_b32_e32 v1, 31, v0
	v_xor_b32_e32 v8, 0xff, v110
	v_lshlrev_b32_e32 v6, 5, v20
	s_add_u32 s4, s11, s4
	s_mul_i32 s20, s22, 0x1100
	v_ashrrev_i32_e32 v7, 31, v6
	s_addc_u32 s5, s10, 0
	s_add_u32 s30, s4, 0x681ef600
	s_addc_u32 s31, s5, 0
	v_lshlrev_b32_e32 v208, 2, v1
	v_cndmask_b32_e64 v1, v8, v110, s[6:7]
	v_lshl_add_u64 v[6:7], v[6:7], 2, s[4:5]
	v_or_b32_e32 v1, s20, v1
	v_lshl_add_u64 v[6:7], v[6:7], 0, v[208:209]
	v_lshlrev_b32_e32 v208, 11, v1
	v_or_b32_e32 v1, 1, v110
	v_xor_b32_e32 v8, 0xfe, v110
	s_mov_b64 s[4:5], 0x681ef600
	v_cndmask_b32_e64 v1, v8, v1, s[6:7]
	v_lshl_add_u64 v[106:107], v[6:7], 0, s[4:5]
	v_lshrrev_b32_e32 v160, 6, v216
	v_and_b32_e32 v162, 31, v216
	v_lshlrev_b32_e32 v160, 7, v160
	v_lshlrev_b32_e32 v163, 11, v110
	v_lshl_or_b32 v160, v162, 2, v160
	v_sub_u32_e32 v162, 0xf800, v163
	v_mov_b32_e32 v161, 0x800
	v_cndmask_b32_e64 v163, v162, v163, s[6:7]
	v_mov_b32_e32 v162, 0xfffff800
	v_add_u32_e32 v160, v160, v163
	v_cndmask_b32_e64 v161, v162, v161, s[6:7]
	v_or_b32_e32 v1, s20, v1
	v_lshl_add_u64 v[6:7], v[106:107], 0, v[208:209]
	v_lshlrev_b32_e32 v208, 11, v1
	v_or_b32_e32 v1, 2, v110
	v_xor_b32_e32 v10, 0xfd, v110
	v_cndmask_b32_e64 v1, v10, v1, s[6:7]
	v_or_b32_e32 v1, s20, v1
	v_lshl_add_u64 v[8:9], v[106:107], 0, v[208:209]
	v_lshlrev_b32_e32 v208, 11, v1
	v_or_b32_e32 v1, 3, v110
	v_xor_b32_e32 v12, 0xfc, v110
	v_cndmask_b32_e64 v1, v12, v1, s[6:7]
	v_or_b32_e32 v1, s20, v1
	v_lshl_add_u64 v[10:11], v[106:107], 0, v[208:209]
	v_lshlrev_b32_e32 v208, 11, v1
	v_or_b32_e32 v1, 8, v110
	v_xor_b32_e32 v14, 0xf7, v110
	v_cndmask_b32_e64 v1, v14, v1, s[6:7]
	v_or_b32_e32 v1, s20, v1
	v_lshl_add_u64 v[12:13], v[106:107], 0, v[208:209]
	v_lshlrev_b32_e32 v208, 11, v1
	v_or_b32_e32 v1, 9, v110
	v_xor_b32_e32 v16, 0xf6, v110
	v_cndmask_b32_e64 v1, v16, v1, s[6:7]
	v_or_b32_e32 v1, s20, v1
	v_lshl_add_u64 v[14:15], v[106:107], 0, v[208:209]
	v_lshlrev_b32_e32 v208, 11, v1
	v_or_b32_e32 v1, 10, v110
	v_xor_b32_e32 v18, 0xf5, v110
	v_cndmask_b32_e64 v1, v18, v1, s[6:7]
	v_or_b32_e32 v1, s20, v1
	v_addc_co_u32_e32 v5, vcc, 0, v3, vcc
	v_lshl_add_u64 v[16:17], v[106:107], 0, v[208:209]
	v_lshlrev_b32_e32 v208, 11, v1
	v_lshl_add_u64 v[18:19], v[106:107], 0, v[208:209]
	global_load_dword v111, v[4:5], off offset:1536
	global_load_dword v148, v[6:7], off
	global_load_dword v147, v[8:9], off
	global_load_dword v144, v[10:11], off
	global_load_dword v142, v[12:13], off
	global_load_dword v140, v[14:15], off
	global_load_dword v138, v[16:17], off
	global_load_dword v137, v[18:19], off
	v_or_b32_e32 v1, 11, v110
	v_xor_b32_e32 v4, 0xf4, v110
	v_cndmask_b32_e64 v1, v4, v1, s[6:7]
	v_or_b32_e32 v1, s20, v1
	v_lshlrev_b32_e32 v208, 11, v1
	v_or_b32_e32 v1, 16, v110
	v_xor_b32_e32 v6, 0xef, v110
	v_cndmask_b32_e64 v1, v6, v1, s[6:7]
	v_or_b32_e32 v1, s20, v1
	v_lshl_add_u64 v[4:5], v[106:107], 0, v[208:209]
	v_lshlrev_b32_e32 v208, 11, v1
	v_or_b32_e32 v1, 17, v110
	v_xor_b32_e32 v8, 0xee, v110
	v_cndmask_b32_e64 v1, v8, v1, s[6:7]
	v_or_b32_e32 v1, s20, v1
	v_lshl_add_u64 v[6:7], v[106:107], 0, v[208:209]
	v_lshlrev_b32_e32 v208, 11, v1
	v_or_b32_e32 v1, 18, v110
	v_xor_b32_e32 v10, 0xed, v110
	v_cndmask_b32_e64 v1, v10, v1, s[6:7]
	v_or_b32_e32 v1, s20, v1
	v_lshl_add_u64 v[8:9], v[106:107], 0, v[208:209]
	v_lshlrev_b32_e32 v208, 11, v1
	v_or_b32_e32 v1, 19, v110
; #define MFMA(a, b, c) __builtin_amdgcn_mfma_f32_32x32x16_bf16((a), (b), (c), 0, 0, 0)
; DI int crow(int r, int h) { return (r & 3) + 8 * (r >> 2) + 4 * h; }
; DI f32x16 zero16() { f32x16 z; for (int i = 0; i < 16; ++i) z[i] = 0.f; return z; }
; DI void stream_of(int n, int cpc, int& m, int& T, int& soff) { if (n < cpc) { m = n; T = CTX; soff = 0; } else { m = n - cpc; T = SEQ; soff = CTX; } }
; DI void hg_scan_block(const Params& p, int chain_in, unsigned char* smem) {
;     ...
;   {
;     int m0_, T0_, so0_; stream_of(0, 8, m0_, T0_, so0_);
; #pragma unroll
;     for (int r = 0; r < 16; ++r) {
;       const int pos = 32 * m0_ + crow(r, h), t = dir ? T0_ - 1 - pos : pos;
;       oc[r] = OHG[(size_t)(b * SP + so0_ + t) * 512 + hd * 128 + 32 * sl + l31];
;     }
;   }
;   f32x16 S[4];
;   for (int i = 0; i < 4; ++i) S[i] = zero16();
; #pragma unroll 1
;   for (int n = 0; n < 136; ++n) {
;     __syncthreads();
; #pragma unroll
;     for (int i = 0; i < 6; ++i) ((u32x4*)sU)[tid + 256 * i] = st[i];
;     if (tid < 128) s_ds[tid] = dsr;
;     __syncthreads();
;     if (n + 1 < 136) {
; #pragma unroll
;       for (int i = 0; i < 6; ++i) st[i] = src[(size_t)(n + 1) * 1536 + tid + 256 * i];
;       dsr = dsg[(size_t)(n + 1) * 128 + (tid & 127)];
;     }
;     float on[16];
;     if (n + 1 < 136) {
;       int m1_, T1_, so1_; stream_of(n + 1, 8, m1_, T1_, so1_);
; #pragma unroll
;       for (int r = 0; r < 16; ++r) {
;         const int pos = 32 * m1_ + crow(r, h), t = dir ? T1_ - 1 - pos : pos;
;         on[r] = OHG[(size_t)(b * SP + so1_ + t) * 512 + hd * 128 + 32 * sl + l31];
;       }
;     } else {
; #pragma unroll
;       for (int r = 0; r < 16; ++r) on[r] = 0.f;
;     }
;     int m, T, soff; stream_of(n, 8, m, T, soff);
;     f32x16 o = zero16();
; #pragma unroll
;     for (int k = 0; k < 4; ++k) {
;       o = MFMA(ld16(s_qhat + ((k * 2 + 0) * 64 + lane) * 8), pack8<0>(S[k]), o);
;       o = MFMA(ld16(s_qhat + ((k * 2 + 1) * 64 + lane) * 8), pack8<1>(S[k]), o);
;     }
	v_xor_b32_e32 v12, 0xec, v110
	v_cndmask_b32_e64 v1, v12, v1, s[6:7]
	v_or_b32_e32 v1, s20, v1
	v_lshl_add_u64 v[10:11], v[106:107], 0, v[208:209]
	v_lshlrev_b32_e32 v208, 11, v1
	v_or_b32_e32 v1, 24, v110
	v_xor_b32_e32 v14, 0xe7, v110
	v_cndmask_b32_e64 v1, v14, v1, s[6:7]
	v_or_b32_e32 v1, s20, v1
	v_lshl_add_u64 v[12:13], v[106:107], 0, v[208:209]
	v_lshlrev_b32_e32 v208, 11, v1
	v_or_b32_e32 v1, 25, v110
	v_xor_b32_e32 v16, 0xe6, v110
	v_cndmask_b32_e64 v1, v16, v1, s[6:7]
	v_or_b32_e32 v1, s20, v1
	v_lshl_add_u64 v[14:15], v[106:107], 0, v[208:209]
	v_lshlrev_b32_e32 v208, 11, v1
	v_or_b32_e32 v1, 26, v110
	v_xor_b32_e32 v18, 0xe5, v110
	v_cndmask_b32_e64 v1, v18, v1, s[6:7]
	v_or_b32_e32 v1, s20, v1
	v_lshl_add_u64 v[16:17], v[106:107], 0, v[208:209]
	v_lshlrev_b32_e32 v208, 11, v1
	v_lshl_add_u64 v[18:19], v[106:107], 0, v[208:209]
	global_load_dword v146, v[4:5], off
	global_load_dword v145, v[6:7], off
	global_load_dword v143, v[8:9], off
	global_load_dword v141, v[10:11], off
	global_load_dword v139, v[12:13], off
	global_load_dword v136, v[14:15], off
	global_load_dword v135, v[16:17], off
	global_load_dword v133, v[18:19], off
	v_or_b32_e32 v1, 27, v110
	v_xor_b32_e32 v4, 0xe4, v110
	v_cndmask_b32_e64 v1, v4, v1, s[6:7]
	v_or_b32_e32 v1, s20, v1
	v_lshlrev_b32_e32 v208, 11, v1
	v_lshl_add_u64 v[4:5], v[106:107], 0, v[208:209]
	global_load_dword v132, v[4:5], off
	v_and_b32_e32 v1, 63, v0
	s_movk_i32 s4, 0x80
	v_lshlrev_b32_e32 v112, 4, v0
	v_cmp_gt_i32_e64 s[4:5], s4, v0
	v_lshlrev_b32_e32 v113, 4, v1
	v_mul_lo_u32 v1, v0, -12
	s_mov_b64 s[8:9], 0x67fcf800
	v_mov_b32_e32 v0, 0
	s_mov_b32 s21, 0
	v_lshl_or_b32 v114, v20, 11, v113
	v_lshlrev_b32_e32 v115, 4, v21
	v_lshl_add_u64 v[108:109], v[2:3], 0, s[8:9]
	s_mov_b64 s[8:9], 0
	v_add_u32_e32 v116, v112, v1
	v_mov_b32_e32 v1, v0
	v_mov_b32_e32 v2, v0
	v_mov_b32_e32 v3, v0
	v_mov_b32_e32 v4, v0
	v_mov_b32_e32 v5, v0
	v_mov_b32_e32 v6, v0
	v_mov_b32_e32 v7, v0
	v_mov_b32_e32 v8, v0
	v_mov_b32_e32 v9, v0
	v_mov_b32_e32 v10, v0
	v_mov_b32_e32 v11, v0
	v_mov_b32_e32 v12, v0
	v_mov_b32_e32 v13, v0
	v_mov_b32_e32 v14, v0
	v_mov_b32_e32 v15, v0
	v_mov_b32_e32 v16, v0
	v_mov_b32_e32 v17, v0
	v_mov_b32_e32 v18, v0
	v_mov_b32_e32 v19, v0
	v_mov_b32_e32 v20, v0
	v_mov_b32_e32 v21, v0
	v_mov_b32_e32 v22, v0
	v_mov_b32_e32 v23, v0
	v_mov_b32_e32 v24, v0
	v_mov_b32_e32 v25, v0
	v_mov_b32_e32 v26, v0
	v_mov_b32_e32 v27, v0
	v_mov_b32_e32 v28, v0
	v_mov_b32_e32 v29, v0
	v_mov_b32_e32 v30, v0
	v_mov_b32_e32 v31, v0
	v_mov_b32_e32 v32, v0
	v_mov_b32_e32 v33, v0
	v_mov_b32_e32 v34, v0
	v_mov_b32_e32 v35, v0
	v_mov_b32_e32 v36, v0
	v_mov_b32_e32 v37, v0
	v_mov_b32_e32 v38, v0
	v_mov_b32_e32 v39, v0
	v_mov_b32_e32 v40, v0
	v_mov_b32_e32 v41, v0
	v_mov_b32_e32 v42, v0
	v_mov_b32_e32 v43, v0
	v_mov_b32_e32 v44, v0
	v_mov_b32_e32 v45, v0
	v_mov_b32_e32 v46, v0
	v_mov_b32_e32 v47, v0
	v_mov_b32_e32 v48, v0
	v_mov_b32_e32 v49, v0
	v_mov_b32_e32 v50, v0
	v_mov_b32_e32 v51, v0
	v_mov_b32_e32 v52, v0
	v_mov_b32_e32 v53, v0
	v_mov_b32_e32 v54, v0
	v_mov_b32_e32 v55, v0
	v_mov_b32_e32 v56, v0
	v_mov_b32_e32 v57, v0
	v_mov_b32_e32 v58, v0
	v_mov_b32_e32 v59, v0
	v_mov_b32_e32 v60, v0
	v_mov_b32_e32 v61, v0
	v_mov_b32_e32 v62, v0
	v_mov_b32_e32 v63, v0
	s_branch .LBB0_498
.LBB0_497:
	ds_read_b128 v[64:67], v113
	ds_read_b128 v[150:153], v113 offset:1024
	v_cvt_pk_bf16_f32 v68, v48, v49
	v_cvt_pk_bf16_f32 v69, v50, v51
	v_cvt_pk_bf16_f32 v70, v52, v53
	v_cvt_pk_bf16_f32 v71, v54, v55
	v_cvt_pk_bf16_f32 v154, v56, v57
	v_cvt_pk_bf16_f32 v155, v58, v59
	v_cvt_pk_bf16_f32 v156, v60, v61
	s_waitcnt lgkmcnt(0)
	v_mfma_f32_32x32x16_bf16 v[64:79], v[64:67], v[68:71], 0
	v_cvt_pk_bf16_f32 v157, v62, v63
	s_cmp_lt_u32 s21, 8
	s_cselect_b32 s11, 0, -8
	s_cselect_b32 s10, 0x100, s95
	s_cselect_b32 s22, 0, 0x100
	s_add_i32 s11, s11, s21
	s_lshl_b32 s11, s11, 5
	v_mfma_f32_32x32x16_bf16 v[64:79], v[150:153], v[154:157], v[64:79]
	ds_read_b128 v[150:153], v113 offset:2048
	v_cvt_pk_bf16_f32 v154, v32, v33
	v_cvt_pk_bf16_f32 v155, v34, v35
	v_cvt_pk_bf16_f32 v156, v36, v37
	v_cvt_pk_bf16_f32 v157, v38, v39
	s_add_i32 s22, s22, s20
	s_add_i32 s26, s22, s11
	s_sub_i32 s27, s10, s11
	s_add_i32 s27, s27, s22
	s_sub_i32 s27, s27, 32
	s_cmp_lg_u64 s[6:7], 0
	s_cselect_b32 s26, s26, s27
	s_lshl_b32 s26, s26, 11
	s_add_u32 s34, s30, s26
	s_addc_u32 s35, s31, 0
	s_add_u32 s8, s8, 0x6000
	s_addc_u32 s9, s9, 0
	s_waitcnt lgkmcnt(0)
	v_mfma_f32_32x32x16_bf16 v[64:79], v[150:153], v[154:157], v[64:79]
	ds_read_b128 v[150:153], v113 offset:3072
	v_cvt_pk_bf16_f32 v154, v40, v41
	v_cvt_pk_bf16_f32 v155, v42, v43
	v_cvt_pk_bf16_f32 v156, v44, v45
	v_cvt_pk_bf16_f32 v157, v46, v47
	s_add_i32 s21, s21, 1
	s_cmp_lg_u32 s8, 0x330000
	s_waitcnt lgkmcnt(0)
	v_mfma_f32_32x32x16_bf16 v[64:79], v[150:153], v[154:157], v[64:79]
	ds_read_b128 v[150:153], v113 offset:4096
	v_cvt_pk_bf16_f32 v154, v16, v17
	v_cvt_pk_bf16_f32 v155, v18, v19
	v_cvt_pk_bf16_f32 v156, v20, v21
	v_cvt_pk_bf16_f32 v157, v22, v23
	s_waitcnt lgkmcnt(0)
	s_nop 0
	v_mfma_f32_32x32x16_bf16 v[64:79], v[150:153], v[154:157], v[64:79]
	ds_read_b128 v[150:153], v113 offset:5120
	v_cvt_pk_bf16_f32 v154, v24, v25
	v_cvt_pk_bf16_f32 v155, v26, v27
	v_cvt_pk_bf16_f32 v156, v28, v29
	v_cvt_pk_bf16_f32 v157, v30, v31
	s_waitcnt lgkmcnt(0)
	s_nop 0
	v_mfma_f32_32x32x16_bf16 v[64:79], v[150:153], v[154:157], v[64:79]
	ds_read_b128 v[150:153], v113 offset:6144
	v_cvt_pk_bf16_f32 v154, v0, v1
	v_cvt_pk_bf16_f32 v155, v2, v3
	v_cvt_pk_bf16_f32 v156, v4, v5
	v_cvt_pk_bf16_f32 v157, v6, v7
	s_waitcnt lgkmcnt(0)
; #define MFMA(a, b, c) __builtin_amdgcn_mfma_f32_32x32x16_bf16((a), (b), (c), 0, 0, 0)
; DI int crow(int r, int h) { return (r & 3) + 8 * (r >> 2) + 4 * h; }
; DI void hg_scan_block(const Params& p, int chain_in, unsigned char* smem) {
;     ...
; #pragma unroll
;     for (int r = 0; r < 16; ++r) {
;       const int pos = 32 * m + crow(r, h), t = dir ? T - 1 - pos : pos;
;       float* dst = OHG + (size_t)(b * SP + soff + t) * 512 + hd * 128 + 32 * sl + l31;
;       *dst = oc[r] + o[r];
;     }
;     const bf16x8 v0 = ld16(s_vT + ((sl * 2 + 0) * 64 + lane) * 8), v1 = ld16(s_vT + ((sl * 2 + 1) * 64 + lane) * 8);
; #pragma unroll
;     for (int k = 0; k < 4; ++k) {
; #pragma unroll
;       for (int g = 0; g < 4; ++g) {
;         const f32x4 d4 = *(const f32x4*)(s_ds + 32 * k + 8 * g + 4 * h);
;         S[k][4 * g] *= d4[0]; S[k][4 * g + 1] *= d4[1]; S[k][4 * g + 2] *= d4[2]; S[k][4 * g + 3] *= d4[3];
;       }
;       S[k] = MFMA(ld16(s_khT + ((k * 2 + 0) * 64 + lane) * 8), v0, S[k]);
;       S[k] = MFMA(ld16(s_khT + ((k * 2 + 1) * 64 + lane) * 8), v1, S[k]);
;     }
; #pragma unroll
;     for (int r = 0; r < 16; ++r) oc[r] = on[r];
	s_nop 0
	v_mfma_f32_32x32x16_bf16 v[64:79], v[150:153], v[154:157], v[64:79]
	ds_read_b128 v[150:153], v113 offset:7168
	v_cvt_pk_bf16_f32 v154, v8, v9
	v_cvt_pk_bf16_f32 v155, v10, v11
	v_cvt_pk_bf16_f32 v156, v12, v13
	v_cvt_pk_bf16_f32 v157, v14, v15
	s_waitcnt lgkmcnt(0)
	s_nop 0
	v_mfma_f32_32x32x16_bf16 v[64:79], v[150:153], v[154:157], v[64:79]
	s_nop 7
	s_nop 3
	v_add_f32_e32 v64, v148, v64
	v_mad_i32_i24 v162, v161, 0, v160
	global_store_dword v162, v64, s[34:35]
	v_add_f32_e32 v64, v147, v65
	v_mad_i32_i24 v163, v161, 1, v160
	global_store_dword v163, v64, s[34:35]
	v_add_f32_e32 v66, v144, v66
	v_mad_i32_i24 v164, v161, 2, v160
	global_store_dword v164, v66, s[34:35]
	v_add_f32_e32 v66, v142, v67
	v_mad_i32_i24 v165, v161, 3, v160
	global_store_dword v165, v66, s[34:35]
	v_add_f32_e32 v66, v140, v68
	v_mad_i32_i24 v162, v161, 8, v160
	global_store_dword v162, v66, s[34:35]
	v_add_f32_e32 v66, v138, v69
	v_mad_i32_i24 v163, v161, 9, v160
	global_store_dword v163, v66, s[34:35]
	v_add_f32_e32 v66, v137, v70
	v_mad_i32_i24 v164, v161, 10, v160
	global_store_dword v164, v66, s[34:35]
	v_add_f32_e32 v66, v146, v71
	v_mad_i32_i24 v165, v161, 11, v160
	global_store_dword v165, v66, s[34:35]
	v_add_f32_e32 v66, v145, v72
	v_mad_i32_i24 v162, v161, 16, v160
	global_store_dword v162, v66, s[34:35]
	v_add_f32_e32 v66, v143, v73
	v_mad_i32_i24 v163, v161, 17, v160
	global_store_dword v163, v66, s[34:35]
	v_add_f32_e32 v66, v141, v74
	v_mad_i32_i24 v164, v161, 18, v160
	global_store_dword v164, v66, s[34:35]
	v_add_f32_e32 v66, v139, v75
	v_mad_i32_i24 v165, v161, 19, v160
	global_store_dword v165, v66, s[34:35]
	v_add_f32_e32 v66, v136, v76
	v_mad_i32_i24 v162, v161, 24, v160
	global_store_dword v162, v66, s[34:35]
	v_add_f32_e32 v66, v135, v77
	v_mad_i32_i24 v163, v161, 25, v160
	global_store_dword v163, v66, s[34:35]
	v_add_f32_e32 v66, v133, v78
	v_mad_i32_i24 v164, v161, 26, v160
	global_store_dword v164, v66, s[34:35]
	v_not_b32_e32 v65, 27
	v_add_f32_e32 v66, v132, v79
	v_mad_i32_i24 v165, v161, 27, v160
	global_store_dword v165, v66, s[34:35]
	ds_read_b128 v[68:71], v114 offset:16384
	ds_read_b128 v[64:67], v114 offset:17408
	ds_read_b128 v[72:75], v115 offset:24576
	ds_read_b128 v[76:79], v115 offset:24608
	ds_read_b128 v[136:139], v115 offset:24640
	ds_read_b128 v[140:143], v115 offset:24672
	s_mov_b64 s[10:11], 0x200
	s_waitcnt lgkmcnt(0)
	v_pk_mul_f32 v[50:51], v[50:51], v[74:75]
	v_pk_mul_f32 v[48:49], v[48:49], v[72:73]
	ds_read_b128 v[72:75], v113 offset:8192
	v_pk_mul_f32 v[62:63], v[62:63], v[142:143]
	v_pk_mul_f32 v[58:59], v[58:59], v[138:139]
	v_pk_mul_f32 v[54:55], v[54:55], v[78:79]
	v_pk_mul_f32 v[60:61], v[60:61], v[140:141]
	v_pk_mul_f32 v[56:57], v[56:57], v[136:137]
	v_pk_mul_f32 v[52:53], v[52:53], v[76:77]
	v_lshl_add_u64 v[108:109], v[108:109], 0, s[10:11]
	s_waitcnt lgkmcnt(0)
	v_mfma_f32_32x32x16_bf16 v[48:63], v[72:75], v[68:71], v[48:63]
	ds_read_b128 v[72:75], v113 offset:9216
	s_waitcnt lgkmcnt(0)
	v_mfma_f32_32x32x16_bf16 v[48:63], v[72:75], v[64:67], v[48:63]
	ds_read_b128 v[72:75], v115 offset:24704
	ds_read_b128 v[76:79], v115 offset:24736
	ds_read_b128 v[136:139], v115 offset:24768
	ds_read_b128 v[140:143], v115 offset:24800
	s_waitcnt lgkmcnt(3)
	v_pk_mul_f32 v[34:35], v[34:35], v[74:75]
	v_pk_mul_f32 v[32:33], v[32:33], v[72:73]
	ds_read_b128 v[72:75], v113 offset:10240
	s_waitcnt lgkmcnt(1)
	v_pk_mul_f32 v[46:47], v[46:47], v[142:143]
	v_pk_mul_f32 v[42:43], v[42:43], v[138:139]
	v_pk_mul_f32 v[38:39], v[38:39], v[78:79]
	v_pk_mul_f32 v[44:45], v[44:45], v[140:141]
	v_pk_mul_f32 v[40:41], v[40:41], v[136:137]
	v_pk_mul_f32 v[36:37], v[36:37], v[76:77]
	s_waitcnt lgkmcnt(0)
	s_nop 0
	v_mfma_f32_32x32x16_bf16 v[32:47], v[72:75], v[68:71], v[32:47]
	ds_read_b128 v[72:75], v113 offset:11264
	s_waitcnt lgkmcnt(0)
	v_mfma_f32_32x32x16_bf16 v[32:47], v[72:75], v[64:67], v[32:47]
	ds_read_b128 v[72:75], v115 offset:24832
	ds_read_b128 v[76:79], v115 offset:24864
	ds_read_b128 v[136:139], v115 offset:24896
	ds_read_b128 v[140:143], v115 offset:24928
	s_waitcnt lgkmcnt(3)
	v_pk_mul_f32 v[18:19], v[18:19], v[74:75]
	v_pk_mul_f32 v[16:17], v[16:17], v[72:73]
	ds_read_b128 v[72:75], v113 offset:12288
	s_waitcnt lgkmcnt(1)
	v_pk_mul_f32 v[30:31], v[30:31], v[142:143]
	v_pk_mul_f32 v[26:27], v[26:27], v[138:139]
	v_pk_mul_f32 v[22:23], v[22:23], v[78:79]
	v_pk_mul_f32 v[28:29], v[28:29], v[140:141]
	v_pk_mul_f32 v[24:25], v[24:25], v[136:137]
	v_pk_mul_f32 v[20:21], v[20:21], v[76:77]
	s_waitcnt lgkmcnt(0)
	s_nop 0
	v_mfma_f32_32x32x16_bf16 v[16:31], v[72:75], v[68:71], v[16:31]
	ds_read_b128 v[72:75], v113 offset:13312
	s_waitcnt lgkmcnt(0)
	v_mfma_f32_32x32x16_bf16 v[16:31], v[72:75], v[64:67], v[16:31]
	ds_read_b128 v[72:75], v115 offset:24960
	ds_read_b128 v[76:79], v115 offset:24992
	ds_read_b128 v[136:139], v115 offset:25024
	ds_read_b128 v[140:143], v115 offset:25056
	s_waitcnt lgkmcnt(3)
	v_pk_mul_f32 v[2:3], v[2:3], v[74:75]
	v_pk_mul_f32 v[0:1], v[0:1], v[72:73]
	ds_read_b128 v[72:75], v113 offset:14336
	s_waitcnt lgkmcnt(1)
	v_pk_mul_f32 v[14:15], v[14:15], v[142:143]
	v_pk_mul_f32 v[10:11], v[10:11], v[138:139]
	v_pk_mul_f32 v[6:7], v[6:7], v[78:79]
	v_pk_mul_f32 v[12:13], v[12:13], v[140:141]
	v_pk_mul_f32 v[8:9], v[8:9], v[136:137]
	v_pk_mul_f32 v[4:5], v[4:5], v[76:77]
	s_waitcnt lgkmcnt(0)
	v_mfma_f32_32x32x16_bf16 v[0:15], v[72:75], v[68:71], v[0:15]
	ds_read_b128 v[68:71], v113 offset:15360
	s_waitcnt lgkmcnt(0)
	v_mfma_f32_32x32x16_bf16 v[0:15], v[68:71], v[64:67], v[0:15]
	s_waitcnt vmcnt(16)
	v_mov_b32_e32 v132, v134
	v_mov_b32_e32 v133, v131
	v_mov_b32_e32 v135, v130
	v_mov_b32_e32 v145, v125
	v_mov_b32_e32 v146, v124
	v_mov_b32_e32 v144, v119
	v_mov_b32_e32 v147, v118
	v_mov_b32_e32 v148, v117
	v_mov_b32_e32 v136, v129
	v_mov_b32_e32 v139, v128
	v_mov_b32_e32 v141, v127
	v_mov_b32_e32 v143, v126
	v_mov_b32_e32 v137, v123
	v_mov_b32_e32 v138, v122
	v_mov_b32_e32 v140, v121
	v_mov_b32_e32 v142, v120
	s_cbranch_scc0 .LBB0_504

; DI int crow(int r, int h) { return (r & 3) + 8 * (r >> 2) + 4 * h; }
; DI void stream_of(int n, int cpc, int& m, int& T, int& soff) { if (n < cpc) { m = n; T = CTX; soff = 0; } else { m = n - cpc; T = SEQ; soff = CTX; } }
; DI void hg_scan_block(const Params& p, int chain_in, unsigned char* smem) {
;     ...
;     float on[16];
;     if (n + 1 < 136) {
;       int m1_, T1_, so1_; stream_of(n + 1, 8, m1_, T1_, so1_);
; #pragma unroll
;       for (int r = 0; r < 16; ++r) {
;         const int pos = 32 * m1_ + crow(r, h), t = dir ? T1_ - 1 - pos : pos;
;         on[r] = OHG[(size_t)(b * SP + so1_ + t) * 512 + hd * 128 + 32 * sl + l31];
;       }
;     } else {
; #pragma unroll
;       for (int r = 0; r < 16; ++r) on[r] = 0.f;
;     }
.LBB0_502:
	v_mov_b32_e32 v134, 0
	s_andn2_b64 vcc, exec, s[10:11]
	v_mov_b32_e32 v131, 0
	v_mov_b32_e32 v130, 0
	v_mov_b32_e32 v129, 0
	v_mov_b32_e32 v128, 0
	v_mov_b32_e32 v127, 0
	v_mov_b32_e32 v126, 0
	v_mov_b32_e32 v125, 0
	v_mov_b32_e32 v124, 0
	v_mov_b32_e32 v123, 0
	v_mov_b32_e32 v122, 0
	v_mov_b32_e32 v121, 0
	v_mov_b32_e32 v120, 0
	v_mov_b32_e32 v119, 0
	v_mov_b32_e32 v118, 0
	v_mov_b32_e32 v117, 0
	s_cbranch_vccnz .LBB0_497
	s_cmp_lt_u32 s21, 7
	s_cselect_b32 s11, 0, -8
	s_cselect_b32 s10, 0x100, s95
	s_cselect_b32 s23, 0, 0x100
	s_add_i32 s11, s11, s21
	s_lshl_b32 s22, s11, 5
	s_add_i32 s22, s22, 32
	s_add_i32 s11, s23, s20
	s_add_i32 s26, s11, s22
	s_sub_i32 s27, s10, s22
	s_add_i32 s27, s27, s11
	s_sub_i32 s27, s27, 32
	s_cmp_lg_u64 s[6:7], 0
	s_cselect_b32 s26, s26, s27
	s_lshl_b32 s26, s26, 11
	s_add_u32 s36, s30, s26
	s_addc_u32 s37, s31, 0
	v_mad_i32_i24 v162, v161, 0, v160
	global_load_dword v117, v162, s[36:37]
	v_mad_i32_i24 v163, v161, 1, v160
	global_load_dword v118, v163, s[36:37]
	v_mad_i32_i24 v164, v161, 2, v160
	global_load_dword v119, v164, s[36:37]
	v_mad_i32_i24 v165, v161, 3, v160
	global_load_dword v120, v165, s[36:37]
	v_mad_i32_i24 v162, v161, 8, v160
	global_load_dword v121, v162, s[36:37]
	v_mad_i32_i24 v163, v161, 9, v160
	global_load_dword v122, v163, s[36:37]
	v_mad_i32_i24 v164, v161, 10, v160
	global_load_dword v123, v164, s[36:37]
	v_mad_i32_i24 v165, v161, 11, v160
	global_load_dword v124, v165, s[36:37]
	v_mad_i32_i24 v162, v161, 16, v160
	global_load_dword v125, v162, s[36:37]
	v_mad_i32_i24 v163, v161, 17, v160
	global_load_dword v126, v163, s[36:37]
	v_mad_i32_i24 v164, v161, 18, v160
	global_load_dword v127, v164, s[36:37]
	v_mad_i32_i24 v165, v161, 19, v160
	global_load_dword v128, v165, s[36:37]
	v_mad_i32_i24 v162, v161, 24, v160
	global_load_dword v129, v162, s[36:37]
	v_mad_i32_i24 v163, v161, 25, v160
	global_load_dword v130, v163, s[36:37]
	v_mad_i32_i24 v164, v161, 26, v160
	global_load_dword v131, v164, s[36:37]
	v_not_b32_e32 v65, 27
	v_mad_i32_i24 v165, v161, 27, v160
	global_load_dword v134, v165, s[36:37]
	s_branch .LBB0_497

; DI unsigned char* launder_ptr(unsigned char* q) { asm volatile("" : "+s"(q)); return q; }
; DI int opaque_tid() { int t = threadIdx.x; asm volatile("" : "+v"(t)); return t; }
; DI f32x16 zero16() { f32x16 z; for (int i = 0; i < 16; ++i) z[i] = 0.f; return z; }
; DI void dn_scan_block(const Params& p, int chain_in, unsigned char* smem) {
;   int chain = blockIdx.x; asm volatile("" : "+v"(chain)); chain = __builtin_amdgcn_readfirstlane(chain) - chain_in;
;   unsigned char* const WS_ = launder_ptr(p.ws);
;   const int tid = opaque_tid(), lane = tid & 63, sl = tid >> 6, l31 = lane & 31, h = lane >> 5;
;   const int hd = chain & 3, b = (chain >> 2) & 3, dir = chain >> 4;
;   float* ODN = (float*)(WS_ + O_ODN) + (size_t)dir * NTOK * 512;
;   const float* GL = (const float*)(WS_ + O_DNG);
;   bfr* sU = (bfr*)smem;
;   const bfr *s_wneg = sU, *s_qdec = sU + 8192, *s_kdT = sU + 16384, *s_aqk = sU + 24576, *s_u = sU + 28672;
;   const u32x4* src = (const u32x4*)(WS_ + O_DNU) + (size_t)chain * 68 * 4608;
;   u32x4 st[18];
; #pragma unroll
;   for (int i = 0; i < 18; ++i) st[i] = src[tid + 256 * i];
;   f32x16 S[4];
;   for (int i = 0; i < 4; ++i) S[i] = zero16();
.LBB0_505:
	s_andn2_b64 vcc, exec, s[4:5]
	s_cbranch_vccnz .LBB0_510
	v_readlane_b32 s4, v254, 28
	s_mov_b32 s8, 0
	s_nop 5
	v_mov_b32_e32 v0, s4
	s_mov_b64 s[4:5], s[84:85]
	v_readfirstlane_b32 s21, v0
	s_ashr_i32 s6, s21, 4
	s_mul_hi_i32 s7, s6, 0x2200000
	s_mul_i32 s6, s6, 0x2200000
	s_add_u32 s22, s4, s6
	s_addc_u32 s23, s5, s7
	s_mul_i32 s6, s21, 0x4c8000
	v_mov_b32_e32 v0, v216
	s_mul_hi_i32 s7, s21, 0x4c8000
	s_add_u32 s6, s4, s6
	s_addc_u32 s7, s5, s7
	v_ashrrev_i32_e32 v1, 31, v0
	v_lshl_add_u64 v[212:213], v[0:1], 4, s[6:7]
	s_mov_b32 s6, 0x53ccd000
	v_add_co_u32_e32 v2, vcc, s6, v212
	s_mov_b32 s6, 0x53cce000
	s_nop 0
	v_addc_co_u32_e32 v3, vcc, 0, v213, vcc
	v_add_co_u32_e32 v4, vcc, s6, v212
	s_mov_b32 s6, 0x53ccf000
	s_nop 0
	v_addc_co_u32_e32 v5, vcc, 0, v213, vcc
	global_load_dwordx4 v[96:99], v[2:3], off offset:1024
	global_load_dwordx4 v[100:103], v[4:5], off offset:1024
	v_add_co_u32_e32 v2, vcc, s6, v212
	s_mov_b32 s6, 0x53cd0000
	s_nop 0
	v_addc_co_u32_e32 v3, vcc, 0, v213, vcc
	v_add_co_u32_e32 v4, vcc, s6, v212
	s_mov_b32 s6, 0x53cd1000
	s_nop 0
	v_addc_co_u32_e32 v5, vcc, 0, v213, vcc
	global_load_dwordx4 v[104:107], v[2:3], off offset:1024
	global_load_dwordx4 v[108:111], v[4:5], off offset:1024
	v_add_co_u32_e32 v2, vcc, s6, v212
	s_mov_b32 s6, 0x53cd2000
	s_nop 0
	v_addc_co_u32_e32 v3, vcc, 0, v213, vcc
	v_add_co_u32_e32 v4, vcc, s6, v212
	s_mov_b32 s6, 0x53cd3000
	s_nop 0
	v_addc_co_u32_e32 v5, vcc, 0, v213, vcc
	global_load_dwordx4 v[112:115], v[2:3], off offset:1024
	global_load_dwordx4 v[116:119], v[4:5], off offset:1024
	v_add_co_u32_e32 v2, vcc, s6, v212
	s_mov_b32 s6, 0x53cd4000
	s_nop 0
	v_addc_co_u32_e32 v3, vcc, 0, v213, vcc
	v_add_co_u32_e32 v4, vcc, s6, v212
	s_mov_b32 s6, 0x53cd5000
	s_nop 0
	v_addc_co_u32_e32 v5, vcc, 0, v213, vcc
	global_load_dwordx4 v[120:123], v[2:3], off offset:1024
	global_load_dwordx4 v[124:127], v[4:5], off offset:1024
	v_add_co_u32_e32 v2, vcc, s6, v212
	s_mov_b32 s6, 0x53cd6000
	s_nop 0
	v_addc_co_u32_e32 v3, vcc, 0, v213, vcc
	v_add_co_u32_e32 v4, vcc, s6, v212
	s_mov_b32 s6, 0x53cd7000
	s_nop 0
	v_addc_co_u32_e32 v5, vcc, 0, v213, vcc
	global_load_dwordx4 v[128:131], v[2:3], off offset:1024
	global_load_dwordx4 v[132:135], v[4:5], off offset:1024
	v_add_co_u32_e32 v2, vcc, s6, v212
	s_mov_b32 s6, 0x53cd8000
	s_nop 0
	v_addc_co_u32_e32 v3, vcc, 0, v213, vcc
	v_add_co_u32_e32 v4, vcc, s6, v212
	s_mov_b32 s6, 0x53cd9000
	s_nop 0
	v_addc_co_u32_e32 v5, vcc, 0, v213, vcc
	global_load_dwordx4 v[136:139], v[2:3], off offset:1024
	global_load_dwordx4 v[140:143], v[4:5], off offset:1024
	v_add_co_u32_e32 v2, vcc, s6, v212
	s_mov_b32 s6, 0x53cda000
	s_nop 0
	v_addc_co_u32_e32 v3, vcc, 0, v213, vcc
	v_add_co_u32_e32 v4, vcc, s6, v212
	s_mov_b32 s6, 0x53cdb000
	s_nop 0
	v_addc_co_u32_e32 v5, vcc, 0, v213, vcc
	global_load_dwordx4 v[144:147], v[2:3], off offset:1024
	global_load_dwordx4 v[148:151], v[4:5], off offset:1024
	v_add_co_u32_e32 v2, vcc, s6, v212
	s_mov_b32 s6, 0x53cdc000
	s_nop 0
	v_addc_co_u32_e32 v3, vcc, 0, v213, vcc
	v_add_co_u32_e32 v4, vcc, s6, v212
	s_mov_b32 s6, 0x53cdd000
	s_nop 0
	v_addc_co_u32_e32 v5, vcc, 0, v213, vcc
	global_load_dwordx4 v[152:155], v[2:3], off offset:1024
	global_load_dwordx4 v[156:159], v[4:5], off offset:1024
	v_add_co_u32_e32 v2, vcc, s6, v212
	s_mov_b32 s6, 0x53cde000
	s_nop 0
	v_addc_co_u32_e32 v3, vcc, 0, v213, vcc
	v_add_co_u32_e32 v4, vcc, s6, v212
	s_bfe_u32 s20, s21, 0x20002
	s_nop 0
	v_addc_co_u32_e32 v5, vcc, 0, v213, vcc
	global_load_dwordx4 v[160:163], v[2:3], off offset:1024
	global_load_dwordx4 v[164:167], v[4:5], off offset:1024
	s_add_u32 s9, s4, 0x5d5cd400
	s_addc_u32 s10, s5, 0
	s_cmp_lt_u32 s21, 16
	s_cselect_b64 s[4:5], -1, 0
	s_lshl_b32 s6, s21, 9
	v_ashrrev_i32_e32 v6, 6, v0
	v_and_b32_e32 v1, 63, v0
	v_and_b32_e32 v2, 31, v0
	v_lshlrev_b32_e32 v223, 4, v0
	v_lshrrev_b32_e32 v0, 3, v0
	s_and_b32 s6, s6, 0x600
	v_lshlrev_b32_e32 v3, 5, v1
	v_lshlrev_b32_e32 v1, 4, v1
	v_and_b32_e32 v225, 4, v0
	v_lshlrev_b32_e32 v0, 5, v6
	s_add_u32 s6, s22, s6
	v_sub_u32_e32 v224, v3, v1
	v_ashrrev_i32_e32 v1, 31, v0
	s_addc_u32 s7, s23, 0
	s_add_u32 s30, s6, 0x5d5cf600
	s_addc_u32 s31, s7, 0
	v_lshl_add_u64 v[0:1], v[0:1], 2, s[6:7]
	v_lshlrev_b32_e32 v208, 2, v2
	v_lshl_add_u64 v[0:1], v[0:1], 0, v[208:209]
	s_mov_b64 s[6:7], 0x5d5cf600
	v_lshl_add_u64 v[214:215], v[0:1], 0, s[6:7]
	v_lshrrev_b32_e32 v230, 6, v216
	v_and_b32_e32 v233, 31, v216
	v_lshlrev_b32_e32 v230, 7, v230
	v_lshlrev_b32_e32 v238, 11, v225
	v_lshl_or_b32 v230, v233, 2, v230
	v_sub_u32_e32 v233, 0xf800, v238
	v_mov_b32_e32 v232, 0x800
	v_cndmask_b32_e64 v238, v233, v238, s[4:5]
	v_mov_b32_e32 v233, 0xfffff800
	v_add_u32_e32 v230, v230, v238
	v_cndmask_b32_e64 v232, v233, v232, s[4:5]
	v_lshl_or_b32 v226, v6, 11, v3
	v_mov_b32_e32 v0, 0
	s_mul_i32 s11, s21, 0x44
	s_mulk_i32 s20, 0x1100
	v_add_u32_e32 v227, 0xe000, v226
	v_or_b32_e32 v228, 1, v225
	v_or_b32_e32 v229, 2, v225
	v_or_b32_e32 v231, 3, v225
	v_or_b32_e32 v235, 8, v225
	v_or_b32_e32 v236, 9, v225
	v_or_b32_e32 v245, 10, v225
	v_or_b32_e32 v246, 11, v225
	v_or_b32_e32 v247, 16, v225
	v_or_b32_e32 v248, 17, v225
	v_or_b32_e32 v249, 18, v225
	v_or_b32_e32 v250, 19, v225
	v_or_b32_e32 v251, 24, v225
	v_or_b32_e32 v252, 25, v225
	v_or_b32_e32 v253, 26, v225
	v_or_b32_e32 v237, 27, v225
	s_mov_b64 s[6:7], 0
	v_mov_b32_e32 v1, v0
	v_mov_b32_e32 v2, v0
	v_mov_b32_e32 v3, v0
	v_mov_b32_e32 v4, v0
	v_mov_b32_e32 v5, v0
	v_mov_b32_e32 v6, v0
	v_mov_b32_e32 v7, v0
	v_mov_b32_e32 v8, v0
	v_mov_b32_e32 v9, v0
	v_mov_b32_e32 v10, v0
	v_mov_b32_e32 v11, v0
	v_mov_b32_e32 v12, v0
	v_mov_b32_e32 v13, v0
	v_mov_b32_e32 v14, v0
	v_mov_b32_e32 v15, v0
	v_mov_b32_e32 v16, v0
	v_mov_b32_e32 v17, v0
	v_mov_b32_e32 v18, v0
	v_mov_b32_e32 v19, v0
	v_mov_b32_e32 v20, v0
	v_mov_b32_e32 v21, v0
	v_mov_b32_e32 v22, v0
	v_mov_b32_e32 v23, v0
	v_mov_b32_e32 v24, v0
	v_mov_b32_e32 v25, v0
	v_mov_b32_e32 v26, v0
	v_mov_b32_e32 v27, v0
	v_mov_b32_e32 v28, v0
	v_mov_b32_e32 v29, v0
	v_mov_b32_e32 v30, v0
	v_mov_b32_e32 v31, v0
	v_mov_b32_e32 v32, v0
	v_mov_b32_e32 v33, v0
	v_mov_b32_e32 v34, v0
	v_mov_b32_e32 v35, v0
	v_mov_b32_e32 v36, v0
	v_mov_b32_e32 v37, v0
	v_mov_b32_e32 v38, v0
	v_mov_b32_e32 v39, v0
	v_mov_b32_e32 v40, v0
	v_mov_b32_e32 v41, v0
	v_mov_b32_e32 v42, v0
	v_mov_b32_e32 v43, v0
	v_mov_b32_e32 v44, v0
	v_mov_b32_e32 v45, v0
	v_mov_b32_e32 v46, v0
	v_mov_b32_e32 v47, v0
	v_mov_b32_e32 v48, v0
	v_mov_b32_e32 v49, v0
	v_mov_b32_e32 v50, v0
	v_mov_b32_e32 v51, v0
	v_mov_b32_e32 v52, v0
	v_mov_b32_e32 v53, v0
	v_mov_b32_e32 v54, v0
	v_mov_b32_e32 v55, v0
	v_mov_b32_e32 v56, v0
	v_mov_b32_e32 v57, v0
	v_mov_b32_e32 v58, v0
	v_mov_b32_e32 v59, v0
	v_mov_b32_e32 v60, v0
	v_mov_b32_e32 v61, v0
	v_mov_b32_e32 v62, v0
	v_mov_b32_e32 v63, v0
	s_branch .LBB0_508
; #define MFMA(a, b, c) __builtin_amdgcn_mfma_f32_32x32x16_bf16((a), (b), (c), 0, 0, 0)
; DI f32x16 zero16() { f32x16 z; for (int i = 0; i < 16; ++i) z[i] = 0.f; return z; }
; DI void stream_of(int n, int cpc, int& m, int& T, int& soff) { if (n < cpc) { m = n; T = CTX; soff = 0; } else { m = n - cpc; T = SEQ; soff = CTX; } }
; DI void dn_scan_block(const Params& p, int chain_in, unsigned char* smem) {
;     ...
;     int m, T, soff; stream_of(n, 4, m, T, soff);
;     f32x16 vn[2];
; #pragma unroll
;     for (int mb = 0; mb < 2; ++mb) {
;       unpack16(s_u + ((mb * 4 + sl) * 64 + lane) * 16, vn[mb]);
; #pragma unroll
;       for (int k = 0; k < 4; ++k) {
;         vn[mb] = MFMA(ld16(s_wneg + (((mb * 4 + k) * 2 + 0) * 64 + lane) * 8), pack8<0>(S[k]), vn[mb]);
;         vn[mb] = MFMA(ld16(s_wneg + (((mb * 4 + k) * 2 + 1) * 64 + lane) * 8), pack8<1>(S[k]), vn[mb]);
;       }
;     }
;     __builtin_amdgcn_sched_barrier(0);
;     bf16x8 vp[2][2];
; #pragma unroll
;     for (int jb = 0; jb < 2; ++jb) { vp[jb][0] = pack8<0>(vn[jb]); vp[jb][1] = pack8<1>(vn[jb]); }
;     __builtin_amdgcn_sched_barrier(0);
; #pragma unroll
;     for (int mb = 0; mb < 2; ++mb) {
;       f32x16 o = zero16();
; #pragma unroll
;       for (int k = 0; k < 4; ++k) {
;         o = MFMA(ld16(s_qdec + (((mb * 4 + k) * 2 + 0) * 64 + lane) * 8), pack8<0>(S[k]), o);
;         o = MFMA(ld16(s_qdec + (((mb * 4 + k) * 2 + 1) * 64 + lane) * 8), pack8<1>(S[k]), o);
;       }
; #pragma unroll
;       for (int jb = 0; jb < 2; ++jb)
; #pragma unroll
;         for (int s = 0; s < 2; ++s) o = MFMA(ld16(s_aqk + (((mb * 2 + jb) * 2 + s) * 64 + lane) * 8), vp[jb][s], o);
.LBB0_507:
	ds_read_b128 v[76:79], v226 offset:57344
	ds_read_b128 v[80:83], v226 offset:57360
	v_cvt_pk_bf16_f32 v176, v48, v49
	v_cvt_pk_bf16_f32 v177, v50, v51
	v_cvt_pk_bf16_f32 v178, v52, v53
	s_waitcnt lgkmcnt(0)
	v_and_b32_e32 v65, 0xffff0000, v76
	v_lshlrev_b32_e32 v64, 16, v76
	v_and_b32_e32 v73, 0xffff0000, v80
	v_lshlrev_b32_e32 v72, 16, v80
	v_and_b32_e32 v67, 0xffff0000, v77
	v_lshlrev_b32_e32 v66, 16, v77
	v_and_b32_e32 v75, 0xffff0000, v81
	v_lshlrev_b32_e32 v74, 16, v81
	v_and_b32_e32 v69, 0xffff0000, v78
	v_lshlrev_b32_e32 v68, 16, v78
	v_and_b32_e32 v77, 0xffff0000, v82
	v_lshlrev_b32_e32 v76, 16, v82
	v_and_b32_e32 v71, 0xffff0000, v79
	v_lshlrev_b32_e32 v70, 16, v79
	v_and_b32_e32 v79, 0xffff0000, v83
	v_lshlrev_b32_e32 v78, 16, v83
	ds_read_b128 v[80:83], v224
	v_cvt_pk_bf16_f32 v179, v54, v55
	v_cvt_pk_bf16_f32 v180, v56, v57
	v_cvt_pk_bf16_f32 v181, v58, v59
	s_waitcnt lgkmcnt(0)
	v_mfma_f32_32x32x16_bf16 v[64:79], v[80:83], v[176:179], v[64:79]
	ds_read_b128 v[80:83], v224 offset:1024
	v_cvt_pk_bf16_f32 v182, v60, v61
	v_cvt_pk_bf16_f32 v183, v62, v63
	v_cvt_pk_bf16_f32 v184, v32, v33
	v_cvt_pk_bf16_f32 v185, v34, v35
	v_cvt_pk_bf16_f32 v186, v36, v37
	v_cvt_pk_bf16_f32 v187, v38, v39
	s_waitcnt lgkmcnt(0)
	v_mfma_f32_32x32x16_bf16 v[64:79], v[80:83], v[180:183], v[64:79]
	ds_read_b128 v[80:83], v224 offset:2048
	v_cvt_pk_bf16_f32 v188, v40, v41
	v_cvt_pk_bf16_f32 v189, v42, v43
	v_cvt_pk_bf16_f32 v190, v44, v45
	v_cvt_pk_bf16_f32 v191, v46, v47
	v_cvt_pk_bf16_f32 v192, v16, v17
	v_cvt_pk_bf16_f32 v193, v18, v19
	s_waitcnt lgkmcnt(0)
	v_mfma_f32_32x32x16_bf16 v[64:79], v[80:83], v[184:187], v[64:79]
	ds_read_b128 v[80:83], v224 offset:3072
	v_cvt_pk_bf16_f32 v194, v20, v21
	v_cvt_pk_bf16_f32 v195, v22, v23
	v_cvt_pk_bf16_f32 v196, v24, v25
	v_cvt_pk_bf16_f32 v197, v26, v27
	v_cvt_pk_bf16_f32 v198, v28, v29
	v_cvt_pk_bf16_f32 v199, v30, v31
	s_waitcnt lgkmcnt(0)
	v_mfma_f32_32x32x16_bf16 v[64:79], v[80:83], v[188:191], v[64:79]
	ds_read_b128 v[80:83], v224 offset:4096
	v_cvt_pk_bf16_f32 v200, v0, v1
	v_cvt_pk_bf16_f32 v201, v2, v3
	v_cvt_pk_bf16_f32 v202, v4, v5
	v_cvt_pk_bf16_f32 v203, v6, v7
	v_cvt_pk_bf16_f32 v204, v8, v9
	v_cvt_pk_bf16_f32 v205, v10, v11
	s_waitcnt lgkmcnt(0)
	v_mfma_f32_32x32x16_bf16 v[64:79], v[80:83], v[192:195], v[64:79]
	ds_read_b128 v[80:83], v224 offset:5120
	v_cvt_pk_bf16_f32 v206, v12, v13
	v_cvt_pk_bf16_f32 v207, v14, v15
	s_cmp_lt_u32 s8, 4
	s_cselect_b32 s22, 0, -4
	s_cselect_b32 s21, 0x100, s95
	s_waitcnt lgkmcnt(0)
	v_mfma_f32_32x32x16_bf16 v[64:79], v[80:83], v[196:199], v[64:79]
	ds_read_b128 v[80:83], v224 offset:6144
	s_waitcnt lgkmcnt(0)
	v_mfma_f32_32x32x16_bf16 v[64:79], v[80:83], v[200:203], v[64:79]
	ds_read_b128 v[80:83], v224 offset:7168
	ds_read_b128 v[92:95], v227 offset:8192
	ds_read_b128 v[168:171], v227 offset:8208
	s_waitcnt lgkmcnt(0)
	v_and_b32_e32 v85, 0xffff0000, v94
	v_and_b32_e32 v89, 0xffff0000, v168
	v_mfma_f32_32x32x16_bf16 v[64:79], v[80:83], v[204:207], v[64:79]
	v_and_b32_e32 v81, 0xffff0000, v92
	v_lshlrev_b32_e32 v80, 16, v92
	v_lshlrev_b32_e32 v88, 16, v168
	v_and_b32_e32 v83, 0xffff0000, v93
	v_lshlrev_b32_e32 v82, 16, v93
	v_and_b32_e32 v91, 0xffff0000, v169
	v_lshlrev_b32_e32 v90, 16, v169
	v_lshlrev_b32_e32 v84, 16, v94
	v_and_b32_e32 v93, 0xffff0000, v170
	v_lshlrev_b32_e32 v92, 16, v170
	v_and_b32_e32 v87, 0xffff0000, v95
	v_lshlrev_b32_e32 v86, 16, v95
	v_and_b32_e32 v95, 0xffff0000, v171
	v_lshlrev_b32_e32 v94, 16, v171
	ds_read_b128 v[168:171], v224 offset:8192
	s_waitcnt lgkmcnt(0)
	v_mfma_f32_32x32x16_bf16 v[80:95], v[168:171], v[176:179], v[80:95]
	ds_read_b128 v[168:171], v224 offset:9216
	s_waitcnt lgkmcnt(0)
	v_mfma_f32_32x32x16_bf16 v[80:95], v[168:171], v[180:183], v[80:95]
	ds_read_b128 v[168:171], v224 offset:10240
	s_waitcnt lgkmcnt(0)
	v_mfma_f32_32x32x16_bf16 v[80:95], v[168:171], v[184:187], v[80:95]
	ds_read_b128 v[168:171], v224 offset:11264
	s_waitcnt lgkmcnt(0)
	v_mfma_f32_32x32x16_bf16 v[80:95], v[168:171], v[188:191], v[80:95]
	ds_read_b128 v[168:171], v224 offset:12288
	s_waitcnt lgkmcnt(0)
	v_mfma_f32_32x32x16_bf16 v[80:95], v[168:171], v[192:195], v[80:95]
	ds_read_b128 v[168:171], v224 offset:13312
	s_waitcnt lgkmcnt(0)
	v_mfma_f32_32x32x16_bf16 v[80:95], v[168:171], v[196:199], v[80:95]
	ds_read_b128 v[168:171], v224 offset:14336
	s_waitcnt lgkmcnt(0)
	v_mfma_f32_32x32x16_bf16 v[80:95], v[168:171], v[200:203], v[80:95]
	ds_read_b128 v[168:171], v224 offset:15360
	s_waitcnt lgkmcnt(0)
	v_mfma_f32_32x32x16_bf16 v[80:95], v[168:171], v[204:207], v[80:95]
	v_cvt_pk_bf16_f32 v172, v64, v65
	v_cvt_pk_bf16_f32 v173, v66, v67
	v_cvt_pk_bf16_f32 v174, v68, v69
	v_cvt_pk_bf16_f32 v175, v70, v71
	v_cvt_pk_bf16_f32 v168, v72, v73
	v_cvt_pk_bf16_f32 v169, v74, v75
	v_cvt_pk_bf16_f32 v170, v76, v77
	v_cvt_pk_bf16_f32 v171, v78, v79
	s_nop 3
	v_cvt_pk_bf16_f32 v80, v80, v81
	v_cvt_pk_bf16_f32 v81, v82, v83
	v_cvt_pk_bf16_f32 v82, v84, v85
	v_cvt_pk_bf16_f32 v83, v86, v87
	v_cvt_pk_bf16_f32 v84, v88, v89
	v_cvt_pk_bf16_f32 v85, v90, v91
	v_cvt_pk_bf16_f32 v86, v92, v93
	v_cvt_pk_bf16_f32 v87, v94, v95
	s_cselect_b32 s24, 0, 0x100
	s_add_i32 s22, s22, s8
	ds_read_b128 v[64:67], v224 offset:16384
	ds_read_b128 v[88:91], v224 offset:17408
	s_lshl_b32 s23, s22, 6
	s_add_i32 s22, s24, s20
	s_waitcnt lgkmcnt(0)
	v_mfma_f32_32x32x16_bf16 v[64:79], v[64:67], v[176:179], 0
	v_mfma_f32_32x32x16_bf16 v[64:79], v[88:91], v[180:183], v[64:79]
	ds_read_b128 v[88:91], v224 offset:18432
	s_waitcnt lgkmcnt(0)
	v_mfma_f32_32x32x16_bf16 v[64:79], v[88:91], v[184:187], v[64:79]
	ds_read_b128 v[88:91], v224 offset:19456
	s_waitcnt lgkmcnt(0)
; #define MFMA(a, b, c) __builtin_amdgcn_mfma_f32_32x32x16_bf16((a), (b), (c), 0, 0, 0)
; DI int crow(int r, int h) { return (r & 3) + 8 * (r >> 2) + 4 * h; }
; DI f32x16 zero16() { f32x16 z; for (int i = 0; i < 16; ++i) z[i] = 0.f; return z; }
; DI void dn_scan_block(const Params& p, int chain_in, unsigned char* smem) {
;     ...
; #pragma unroll
;     for (int mb = 0; mb < 2; ++mb) {
;       f32x16 o = zero16();
; #pragma unroll
;       for (int k = 0; k < 4; ++k) {
;         o = MFMA(ld16(s_qdec + (((mb * 4 + k) * 2 + 0) * 64 + lane) * 8), pack8<0>(S[k]), o);
;         o = MFMA(ld16(s_qdec + (((mb * 4 + k) * 2 + 1) * 64 + lane) * 8), pack8<1>(S[k]), o);
;       }
; #pragma unroll
;       for (int jb = 0; jb < 2; ++jb)
; #pragma unroll
;         for (int s = 0; s < 2; ++s) o = MFMA(ld16(s_aqk + (((mb * 2 + jb) * 2 + s) * 64 + lane) * 8), vp[jb][s], o);
; #pragma unroll
;       for (int r = 0; r < 16; ++r) {
;         const int pos = 64 * m + 32 * mb + crow(r, h), t = dir ? T - 1 - pos : pos;
;         ODN[(size_t)(b * SP + soff + t) * 512 + hd * 128 + 32 * sl + l31] = o[r];
;       }
;       __builtin_amdgcn_sched_barrier(0);
	v_mfma_f32_32x32x16_bf16 v[64:79], v[88:91], v[188:191], v[64:79]
	ds_read_b128 v[88:91], v224 offset:20480
	s_waitcnt lgkmcnt(0)
	v_mfma_f32_32x32x16_bf16 v[64:79], v[88:91], v[192:195], v[64:79]
	ds_read_b128 v[88:91], v224 offset:21504
	s_waitcnt lgkmcnt(0)
	v_mfma_f32_32x32x16_bf16 v[64:79], v[88:91], v[196:199], v[64:79]
	ds_read_b128 v[88:91], v224 offset:22528
	s_waitcnt lgkmcnt(0)
	v_mfma_f32_32x32x16_bf16 v[64:79], v[88:91], v[200:203], v[64:79]
	ds_read_b128 v[88:91], v224 offset:23552
	s_waitcnt lgkmcnt(0)
	v_mfma_f32_32x32x16_bf16 v[64:79], v[88:91], v[204:207], v[64:79]
	ds_read_b128 v[88:91], v224 offset:49152
	s_waitcnt lgkmcnt(0)
	v_mfma_f32_32x32x16_bf16 v[64:79], v[88:91], v[172:175], v[64:79]
	ds_read_b128 v[88:91], v224 offset:50176
	s_waitcnt lgkmcnt(0)
	v_mfma_f32_32x32x16_bf16 v[64:79], v[88:91], v[168:171], v[64:79]
	ds_read_b128 v[88:91], v224 offset:51200
	s_waitcnt lgkmcnt(0)
	v_mfma_f32_32x32x16_bf16 v[64:79], v[88:91], v[80:83], v[64:79]
	ds_read_b128 v[88:91], v224 offset:52224
	s_waitcnt lgkmcnt(0)
	v_mfma_f32_32x32x16_bf16 v[64:79], v[88:91], v[84:87], v[64:79]
	s_add_i32 s26, s22, s23
	s_sub_i32 s27, s21, s23
	s_add_i32 s27, s27, s22
	s_sub_i32 s27, s27, 32
	s_cmp_lg_u64 s[4:5], 0
	s_cselect_b32 s26, s26, s27
	s_lshl_b32 s26, s26, 11
	s_add_u32 s34, s30, s26
	s_addc_u32 s35, s31, 0
	s_nop 3
	v_mad_i32_i24 v233, v232, 0, v230
	global_store_dword v233, v64, s[34:35]
	v_mad_i32_i24 v238, v232, 1, v230
	global_store_dword v238, v65, s[34:35]
	v_mad_i32_i24 v239, v232, 2, v230
	global_store_dword v239, v66, s[34:35]
	v_mad_i32_i24 v240, v232, 3, v230
	global_store_dword v240, v67, s[34:35]
	v_mad_i32_i24 v233, v232, 8, v230
	global_store_dword v233, v68, s[34:35]
	v_mad_i32_i24 v238, v232, 9, v230
	global_store_dword v238, v69, s[34:35]
	v_mad_i32_i24 v239, v232, 10, v230
	global_store_dword v239, v70, s[34:35]
	v_mad_i32_i24 v240, v232, 11, v230
	global_store_dword v240, v71, s[34:35]
	v_mad_i32_i24 v233, v232, 16, v230
	global_store_dword v233, v72, s[34:35]
	v_mad_i32_i24 v238, v232, 17, v230
	global_store_dword v238, v73, s[34:35]
	v_mad_i32_i24 v239, v232, 18, v230
	global_store_dword v239, v74, s[34:35]
	v_mad_i32_i24 v240, v232, 19, v230
	global_store_dword v240, v75, s[34:35]
	v_mad_i32_i24 v233, v232, 24, v230
	global_store_dword v233, v76, s[34:35]
	v_mad_i32_i24 v238, v232, 25, v230
	global_store_dword v238, v77, s[34:35]
	v_mad_i32_i24 v239, v232, 26, v230
	global_store_dword v239, v78, s[34:35]
	v_mad_i32_i24 v240, v232, 27, v230
	global_store_dword v240, v79, s[34:35]
	ds_read_b128 v[64:67], v224 offset:24576
	ds_read_b128 v[88:91], v224 offset:25600
	s_or_b32 s23, s23, 32
	s_waitcnt lgkmcnt(0)
	v_mfma_f32_32x32x16_bf16 v[64:79], v[64:67], v[176:179], 0
	v_mfma_f32_32x32x16_bf16 v[64:79], v[88:91], v[180:183], v[64:79]
	ds_read_b128 v[88:91], v224 offset:26624
	s_waitcnt lgkmcnt(0)
	v_mfma_f32_32x32x16_bf16 v[64:79], v[88:91], v[184:187], v[64:79]
	ds_read_b128 v[88:91], v224 offset:27648
	s_waitcnt lgkmcnt(0)
	v_mfma_f32_32x32x16_bf16 v[64:79], v[88:91], v[188:191], v[64:79]
	ds_read_b128 v[88:91], v224 offset:28672
	s_waitcnt lgkmcnt(0)
	v_mfma_f32_32x32x16_bf16 v[64:79], v[88:91], v[192:195], v[64:79]
	ds_read_b128 v[88:91], v224 offset:29696
	s_waitcnt lgkmcnt(0)
	v_mfma_f32_32x32x16_bf16 v[64:79], v[88:91], v[196:199], v[64:79]
	ds_read_b128 v[88:91], v224 offset:30720
	s_waitcnt lgkmcnt(0)
	v_mfma_f32_32x32x16_bf16 v[64:79], v[88:91], v[200:203], v[64:79]
	ds_read_b128 v[88:91], v224 offset:31744
	s_waitcnt lgkmcnt(0)
	v_mfma_f32_32x32x16_bf16 v[64:79], v[88:91], v[204:207], v[64:79]
	ds_read_b128 v[88:91], v224 offset:53248
	s_waitcnt lgkmcnt(0)
	v_mfma_f32_32x32x16_bf16 v[64:79], v[88:91], v[172:175], v[64:79]
	ds_read_b128 v[88:91], v224 offset:54272
	s_waitcnt lgkmcnt(0)
	v_mfma_f32_32x32x16_bf16 v[64:79], v[88:91], v[168:171], v[64:79]
	ds_read_b128 v[88:91], v224 offset:55296
	s_waitcnt lgkmcnt(0)
	v_mfma_f32_32x32x16_bf16 v[64:79], v[88:91], v[80:83], v[64:79]
	ds_read_b128 v[88:91], v224 offset:56320
	s_waitcnt lgkmcnt(0)
; #define MFMA(a, b, c) __builtin_amdgcn_mfma_f32_32x32x16_bf16((a), (b), (c), 0, 0, 0)
; DI int crow(int r, int h) { return (r & 3) + 8 * (r >> 2) + 4 * h; }
; DI void dn_scan_block(const Params& p, int chain_in, unsigned char* smem) {
;     ...
; #pragma unroll
;       for (int r = 0; r < 16; ++r) {
;         const int pos = 64 * m + 32 * mb + crow(r, h), t = dir ? T - 1 - pos : pos;
;         ODN[(size_t)(b * SP + soff + t) * 512 + hd * 128 + 32 * sl + l31] = o[r];
;       }
;       __builtin_amdgcn_sched_barrier(0);
;     }
; #pragma unroll
;     for (int k = 0; k < 4; ++k) {
; #pragma unroll
;       for (int r = 0; r < 16; ++r) S[k][r] *= gl;
; #pragma unroll
;       for (int jb = 0; jb < 2; ++jb)
; #pragma unroll
;         for (int s = 0; s < 2; ++s) S[k] = MFMA(ld16(s_kdT + (((k * 2 + jb) * 2 + s) * 64 + lane) * 8), vp[jb][s], S[k]);
;     }
	v_mfma_f32_32x32x16_bf16 v[64:79], v[88:91], v[84:87], v[64:79]
	s_add_i32 s26, s22, s23
	s_sub_i32 s27, s21, s23
	s_add_i32 s27, s27, s22
	s_sub_i32 s27, s27, 32
	s_cmp_lg_u64 s[4:5], 0
	s_cselect_b32 s26, s26, s27
	s_lshl_b32 s26, s26, 11
	s_add_u32 s34, s30, s26
	s_addc_u32 s35, s31, 0
	s_nop 3
	v_mad_i32_i24 v233, v232, 0, v230
	global_store_dword v233, v64, s[34:35]
	v_mad_i32_i24 v238, v232, 1, v230
	global_store_dword v238, v65, s[34:35]
	v_mad_i32_i24 v239, v232, 2, v230
	global_store_dword v239, v66, s[34:35]
	v_mad_i32_i24 v240, v232, 3, v230
	global_store_dword v240, v67, s[34:35]
	v_mad_i32_i24 v233, v232, 8, v230
	global_store_dword v233, v68, s[34:35]
	v_mad_i32_i24 v238, v232, 9, v230
	global_store_dword v238, v69, s[34:35]
	v_mad_i32_i24 v239, v232, 10, v230
	global_store_dword v239, v70, s[34:35]
	v_mad_i32_i24 v240, v232, 11, v230
	global_store_dword v240, v71, s[34:35]
	v_mad_i32_i24 v233, v232, 16, v230
	global_store_dword v233, v72, s[34:35]
	v_mad_i32_i24 v238, v232, 17, v230
	global_store_dword v238, v73, s[34:35]
	v_mad_i32_i24 v239, v232, 18, v230
	global_store_dword v239, v74, s[34:35]
	v_mad_i32_i24 v240, v232, 19, v230
	global_store_dword v240, v75, s[34:35]
	v_mad_i32_i24 v233, v232, 24, v230
	global_store_dword v233, v76, s[34:35]
	v_mad_i32_i24 v238, v232, 25, v230
	global_store_dword v238, v77, s[34:35]
	v_mad_i32_i24 v239, v232, 26, v230
	global_store_dword v239, v78, s[34:35]
	v_mad_i32_i24 v240, v232, 27, v230
	global_store_dword v240, v79, s[34:35]
	ds_read_b128 v[64:67], v224 offset:32768
	v_pk_mul_f32 v[62:63], v[62:63], v[208:209] op_sel_hi:[1,0]
	v_pk_mul_f32 v[60:61], v[60:61], v[208:209] op_sel_hi:[1,0]
	v_pk_mul_f32 v[58:59], v[58:59], v[208:209] op_sel_hi:[1,0]
	v_pk_mul_f32 v[56:57], v[56:57], v[208:209] op_sel_hi:[1,0]
	v_pk_mul_f32 v[54:55], v[54:55], v[208:209] op_sel_hi:[1,0]
	v_pk_mul_f32 v[52:53], v[52:53], v[208:209] op_sel_hi:[1,0]
	v_pk_mul_f32 v[50:51], v[50:51], v[208:209] op_sel_hi:[1,0]
	v_pk_mul_f32 v[48:49], v[48:49], v[208:209] op_sel_hi:[1,0]
	v_pk_mul_f32 v[46:47], v[46:47], v[208:209] op_sel_hi:[1,0]
	v_pk_mul_f32 v[44:45], v[44:45], v[208:209] op_sel_hi:[1,0]
	s_waitcnt lgkmcnt(0)
	v_mfma_f32_32x32x16_bf16 v[48:63], v[64:67], v[172:175], v[48:63]
	ds_read_b128 v[64:67], v224 offset:33792
	v_mul_f32_e64 v42, v42, v208
	v_mul_f32_e64 v43, v43, v208
	v_mul_f32_e64 v40, v40, v208
	v_mul_f32_e64 v41, v41, v208
	v_pk_mul_f32 v[38:39], v[38:39], v[208:209] op_sel_hi:[1,0]
	v_pk_mul_f32 v[36:37], v[36:37], v[208:209] op_sel_hi:[1,0]
	v_pk_mul_f32 v[34:35], v[34:35], v[208:209] op_sel_hi:[1,0]
	v_pk_mul_f32 v[32:33], v[32:33], v[208:209] op_sel_hi:[1,0]
	s_waitcnt lgkmcnt(0)
	v_mfma_f32_32x32x16_bf16 v[48:63], v[64:67], v[168:171], v[48:63]
	ds_read_b128 v[64:67], v224 offset:34816
	v_mul_f32_e64 v30, v30, v208
	v_mul_f32_e64 v31, v31, v208
	v_mul_f32_e64 v28, v28, v208
	v_mul_f32_e64 v29, v29, v208
	v_pk_mul_f32 v[26:27], v[26:27], v[208:209] op_sel_hi:[1,0]
	v_pk_mul_f32 v[24:25], v[24:25], v[208:209] op_sel_hi:[1,0]
	v_pk_mul_f32 v[22:23], v[22:23], v[208:209] op_sel_hi:[1,0]
	v_pk_mul_f32 v[20:21], v[20:21], v[208:209] op_sel_hi:[1,0]
	s_waitcnt lgkmcnt(0)
	v_mfma_f32_32x32x16_bf16 v[48:63], v[64:67], v[80:83], v[48:63]
	ds_read_b128 v[64:67], v224 offset:35840
	v_mul_f32_e64 v18, v18, v208
	v_mul_f32_e64 v19, v19, v208
	v_mul_f32_e64 v16, v16, v208
	v_mul_f32_e64 v17, v17, v208
	v_pk_mul_f32 v[14:15], v[14:15], v[208:209] op_sel_hi:[1,0]
	v_pk_mul_f32 v[12:13], v[12:13], v[208:209] op_sel_hi:[1,0]
	v_pk_mul_f32 v[10:11], v[10:11], v[208:209] op_sel_hi:[1,0]
	v_pk_mul_f32 v[8:9], v[8:9], v[208:209] op_sel_hi:[1,0]
	s_waitcnt lgkmcnt(0)
	v_mfma_f32_32x32x16_bf16 v[48:63], v[64:67], v[84:87], v[48:63]
	ds_read_b128 v[64:67], v224 offset:36864
	v_mul_f32_e64 v6, v6, v208
	v_mul_f32_e64 v7, v7, v208
	v_mul_f32_e64 v4, v4, v208
	v_mul_f32_e64 v5, v5, v208
	v_pk_mul_f32 v[2:3], v[2:3], v[208:209] op_sel_hi:[1,0]
	v_pk_mul_f32 v[0:1], v[0:1], v[208:209] op_sel_hi:[1,0]
	s_add_u32 s6, s6, 0x12000
	s_addc_u32 s7, s7, 0
	s_waitcnt lgkmcnt(0)
	v_mfma_f32_32x32x16_bf16 v[32:47], v[64:67], v[172:175], v[32:47]
	ds_read_b128 v[64:67], v224 offset:37888
	s_add_i32 s8, s8, 1
	s_cmp_eq_u32 s6, 0x4c8000
	s_waitcnt lgkmcnt(0)
	v_mfma_f32_32x32x16_bf16 v[32:47], v[64:67], v[168:171], v[32:47]
	ds_read_b128 v[64:67], v224 offset:38912
	s_waitcnt lgkmcnt(0)
	v_mfma_f32_32x32x16_bf16 v[32:47], v[64:67], v[80:83], v[32:47]
	ds_read_b128 v[64:67], v224 offset:39936
	s_waitcnt lgkmcnt(0)
	v_mfma_f32_32x32x16_bf16 v[32:47], v[64:67], v[84:87], v[32:47]
	ds_read_b128 v[64:67], v224 offset:40960
	s_waitcnt lgkmcnt(0)
	v_mfma_f32_32x32x16_bf16 v[16:31], v[64:67], v[172:175], v[16:31]
	ds_read_b128 v[64:67], v224 offset:41984
	s_waitcnt lgkmcnt(0)
	v_mfma_f32_32x32x16_bf16 v[16:31], v[64:67], v[168:171], v[16:31]
	ds_read_b128 v[64:67], v224 offset:43008
	s_waitcnt lgkmcnt(0)
	v_mfma_f32_32x32x16_bf16 v[16:31], v[64:67], v[80:83], v[16:31]
	ds_read_b128 v[64:67], v224 offset:44032
	s_waitcnt lgkmcnt(0)
	v_mfma_f32_32x32x16_bf16 v[16:31], v[64:67], v[84:87], v[16:31]
	ds_read_b128 v[64:67], v224 offset:45056
	s_waitcnt lgkmcnt(0)
	v_mfma_f32_32x32x16_bf16 v[0:15], v[64:67], v[172:175], v[0:15]
	ds_read_b128 v[64:67], v224 offset:46080
	s_waitcnt lgkmcnt(0)
	v_mfma_f32_32x32x16_bf16 v[0:15], v[64:67], v[168:171], v[0:15]
	ds_read_b128 v[64:67], v224 offset:47104
	s_waitcnt lgkmcnt(0)
	v_mfma_f32_32x32x16_bf16 v[0:15], v[64:67], v[80:83], v[0:15]
	ds_read_b128 v[64:67], v224 offset:48128
	s_waitcnt lgkmcnt(0)
	v_mfma_f32_32x32x16_bf16 v[0:15], v[64:67], v[84:87], v[0:15]
	s_cbranch_scc1 .LBB0_510
